# P6 unit-boundary vmcnt(0) drains relaxed to vmcnt(8): epilogue stores stay in flight into next unit
# speedup vs baseline: 1.0058x; 1.0058x over previous
.LBB0_681:
	s_andn2_b64 vcc, exec, s[0:1]
	s_waitcnt vmcnt(8)
	v_mov_b32_e32 v166, v153
	v_mov_b32_e32 v165, v154
	v_mov_b32_e32 v164, v155
	v_mov_b32_e32 v163, v156
	v_mov_b32_e32 v162, v157
	v_mov_b32_e32 v161, v158
	v_mov_b32_e32 v152, v159
	v_mov_b32_e32 v149, v160
	s_mov_b32 s18, s14
	s_mov_b32 s36, s20
	s_mov_b64 s[38:39], s[24:25]
	s_mov_b64 s[40:41], s[22:23]
	s_cbranch_vccz .LBB0_693

.LBB0_684:
	s_ashr_i32 s21, s20, 31
	s_lshl_b64 s[22:23], s[20:21], 19
	s_add_u32 s22, s4, s22
	s_addc_u32 s23, s5, s23
	s_and_b64 s[24:25], s[0:1], exec
	s_cselect_b32 s19, s23, s41
	s_cselect_b32 s21, s22, s40
	s_ashr_i32 s15, s14, 31
	s_lshl_b64 s[24:25], s[14:15], 19
	s_add_u32 s24, s72, s24
	s_addc_u32 s25, s73, s25
	s_and_b64 s[42:43], s[0:1], exec
	s_cselect_b32 s15, s25, s39
	s_cselect_b32 s33, s24, s38
	v_lshl_add_u32 v0, s20, 8, v146
	s_add_u32 s57, s38, 0x100
	v_ashrrev_i32_e32 v1, 31, v0
	s_addc_u32 s58, s39, 0
	v_lshl_add_u64 v[144:145], v[0:1], 2, s[8:9]
	s_add_u32 s38, s40, 0x40080
	v_mov_b32_e32 v0, 0
	s_addc_u32 s39, s41, 0
	s_mov_b32 s59, -2
	s_waitcnt vmcnt(8)
	v_mov_b32_e32 v153, v166
	v_mov_b32_e32 v154, v165
	v_mov_b32_e32 v155, v164
	v_mov_b32_e32 v156, v163
	v_mov_b32_e32 v157, v162
	v_mov_b32_e32 v158, v161
	v_mov_b32_e32 v159, v152
	v_mov_b32_e32 v160, v149
	v_mov_b32_e32 v1, v0
	v_mov_b32_e32 v2, v0
	v_mov_b32_e32 v3, v0
	v_mov_b32_e32 v8, v0
	v_mov_b32_e32 v9, v0
	v_mov_b32_e32 v10, v0
	v_mov_b32_e32 v11, v0
	v_mov_b32_e32 v16, v0
	v_mov_b32_e32 v17, v0
	v_mov_b32_e32 v18, v0
	v_mov_b32_e32 v19, v0
	v_mov_b32_e32 v24, v0
	v_mov_b32_e32 v25, v0
	v_mov_b32_e32 v26, v0
	v_mov_b32_e32 v27, v0
	v_mov_b32_e32 v32, v0
	v_mov_b32_e32 v33, v0
	v_mov_b32_e32 v34, v0
	v_mov_b32_e32 v35, v0
	v_mov_b32_e32 v40, v0
	v_mov_b32_e32 v41, v0
	v_mov_b32_e32 v42, v0
	v_mov_b32_e32 v43, v0
	v_mov_b32_e32 v48, v0
	v_mov_b32_e32 v49, v0
	v_mov_b32_e32 v50, v0
	v_mov_b32_e32 v51, v0
	v_mov_b32_e32 v56, v0
	v_mov_b32_e32 v57, v0
	v_mov_b32_e32 v58, v0
	v_mov_b32_e32 v59, v0
	v_mov_b32_e32 v4, v0
	v_mov_b32_e32 v5, v0
	v_mov_b32_e32 v6, v0
	v_mov_b32_e32 v7, v0
	v_mov_b32_e32 v12, v0
	v_mov_b32_e32 v13, v0
	v_mov_b32_e32 v14, v0
	v_mov_b32_e32 v15, v0
	v_mov_b32_e32 v20, v0
	v_mov_b32_e32 v21, v0
	v_mov_b32_e32 v22, v0
	v_mov_b32_e32 v23, v0
	v_mov_b32_e32 v28, v0
	v_mov_b32_e32 v29, v0
	v_mov_b32_e32 v30, v0
	v_mov_b32_e32 v31, v0
	v_mov_b32_e32 v36, v0
	v_mov_b32_e32 v37, v0
	v_mov_b32_e32 v38, v0
	v_mov_b32_e32 v39, v0
	v_mov_b32_e32 v44, v0
	v_mov_b32_e32 v45, v0
	v_mov_b32_e32 v46, v0
	v_mov_b32_e32 v47, v0
	v_mov_b32_e32 v52, v0
	v_mov_b32_e32 v53, v0
	v_mov_b32_e32 v54, v0
	v_mov_b32_e32 v55, v0
	v_mov_b32_e32 v60, v0
	v_mov_b32_e32 v61, v0
	v_mov_b32_e32 v62, v0
	v_mov_b32_e32 v63, v0
	v_mov_b32_e32 v64, v0
	v_mov_b32_e32 v65, v0
	v_mov_b32_e32 v66, v0
	v_mov_b32_e32 v67, v0
	v_mov_b32_e32 v72, v0
	v_mov_b32_e32 v73, v0
	v_mov_b32_e32 v74, v0
	v_mov_b32_e32 v75, v0
	v_mov_b32_e32 v80, v0
	v_mov_b32_e32 v81, v0
	v_mov_b32_e32 v82, v0
	v_mov_b32_e32 v83, v0
	v_mov_b32_e32 v88, v0
	v_mov_b32_e32 v89, v0
	v_mov_b32_e32 v90, v0
	v_mov_b32_e32 v91, v0
	v_mov_b32_e32 v96, v0
	v_mov_b32_e32 v97, v0
	v_mov_b32_e32 v98, v0
	v_mov_b32_e32 v99, v0
	v_mov_b32_e32 v104, v0
	v_mov_b32_e32 v105, v0
	v_mov_b32_e32 v106, v0
	v_mov_b32_e32 v107, v0
	v_mov_b32_e32 v112, v0
	v_mov_b32_e32 v113, v0
	v_mov_b32_e32 v114, v0
	v_mov_b32_e32 v115, v0
	v_mov_b32_e32 v120, v0
	v_mov_b32_e32 v121, v0
	v_mov_b32_e32 v122, v0
	v_mov_b32_e32 v123, v0
	v_mov_b32_e32 v68, v0
	v_mov_b32_e32 v69, v0
	v_mov_b32_e32 v70, v0
	v_mov_b32_e32 v71, v0
	v_mov_b32_e32 v76, v0
	v_mov_b32_e32 v77, v0
	v_mov_b32_e32 v78, v0
	v_mov_b32_e32 v79, v0
	v_mov_b32_e32 v84, v0
	v_mov_b32_e32 v85, v0
	v_mov_b32_e32 v86, v0
	v_mov_b32_e32 v87, v0
	v_mov_b32_e32 v92, v0
	v_mov_b32_e32 v93, v0
	v_mov_b32_e32 v94, v0
	v_mov_b32_e32 v95, v0
	v_mov_b32_e32 v100, v0
	v_mov_b32_e32 v101, v0
	v_mov_b32_e32 v102, v0
	v_mov_b32_e32 v103, v0
	v_mov_b32_e32 v108, v0
	v_mov_b32_e32 v109, v0
	v_mov_b32_e32 v110, v0
	v_mov_b32_e32 v111, v0
	v_mov_b32_e32 v116, v0
	v_mov_b32_e32 v117, v0
	v_mov_b32_e32 v118, v0
	v_mov_b32_e32 v119, v0
	v_mov_b32_e32 v124, v0
	v_mov_b32_e32 v125, v0
	v_mov_b32_e32 v126, v0
	v_mov_b32_e32 v127, v0
	s_branch .LBB0_686
